# v141 with the C-init emission order fixed: the tuple the first QK MFMA reads as C is finished first (keeps the 2 wait states VALU write -> MFMA read; v141 had 1 in one body)
# speedup vs baseline: 1.0030x; 1.0009x over previous
.LBB0_595:
	s_add_i32 s36, s21, 0xffff4000
	s_and_b32 s36, s36, 0x8000
	s_add_i32 s36, s36, 0
	v_add_u32_e32 v0, s36, v210
	ds_read_b128 v[2:5], v0
	ds_read_b128 v[8:11], v0 offset:8192
	v_cvt_f32_u32_e32 v0, s28
	v_add_u32_e32 v7, s36, v211
	ds_read_b128 v[12:15], v7
	ds_read_b128 v[224:227], v7 offset:8192
	v_sub_f32_e32 v0, v0, v205
	v_fma_f32 v96, v166, v0, -v169
	v_add_f32_e32 v97, v166, v96
	v_add_f32_e32 v98, v167, v96
	v_add_f32_e32 v99, v186, v96
	v_add_f32_e32 v100, v187, v96
	v_add_f32_e32 v101, v166, v100
	v_add_f32_e32 v102, v167, v100
	v_add_f32_e32 v103, v186, v100
	v_add_f32_e32 v104, v187, v100
	v_add_f32_e32 v105, v166, v104
	v_add_f32_e32 v106, v167, v104
	v_add_f32_e32 v107, v186, v104
	v_add_f32_e32 v108, v187, v104
	v_add_f32_e32 v109, v166, v108
	v_add_f32_e32 v110, v167, v108
	v_add_f32_e32 v111, v186, v108
	v_add_f32_e32 v80, v168, v96
	v_add_f32_e32 v81, v166, v80
	v_add_f32_e32 v82, v167, v80
	v_add_f32_e32 v83, v186, v80
	v_add_f32_e32 v84, v187, v80
	v_add_f32_e32 v85, v166, v84
	v_add_f32_e32 v86, v167, v84
	v_add_f32_e32 v87, v186, v84
	v_add_f32_e32 v88, v187, v84
	v_add_f32_e32 v89, v166, v88
	v_add_f32_e32 v90, v167, v88
	v_add_f32_e32 v91, v186, v88
	v_add_f32_e32 v92, v187, v88
	v_add_f32_e32 v93, v166, v92
	v_add_f32_e32 v94, v167, v92
	v_add_f32_e32 v95, v186, v92
	s_waitcnt lgkmcnt(3)
	v_mfma_f32_32x32x16_bf16 v[96:111], v[2:5], v[144:147], v[96:111]
	v_add_u32_e32 v0, s36, v212
	v_exp_f32_e32 v7, v112
	v_exp_f32_e32 v112, v128
	v_exp_f32_e32 v160, v129
	v_exp_f32_e32 v116, v116
	v_exp_f32_e32 v128, v132
	v_exp_f32_e32 v132, v115
	s_waitcnt lgkmcnt(2)
	v_mfma_f32_32x32x16_bf16 v[80:95], v[8:11], v[144:147], v[80:95]
	ds_read_b128 v[2:5], v0
	ds_read_b128 v[8:11], v0 offset:8192
	v_add_u32_e32 v0, s36, v213
	v_exp_f32_e32 v162, v131
	v_exp_f32_e32 v115, v134
	v_exp_f32_e32 v134, v117
	v_exp_f32_e32 v164, v133
	v_exp_f32_e32 v198, v119
	s_waitcnt lgkmcnt(3)
	v_mfma_f32_32x32x16_bf16 v[96:111], v[12:15], v[148:151], v[96:111]
	ds_read_b128 v[12:15], v0
	ds_read_b128 v[228:231], v0 offset:8192
	v_add_u32_e32 v0, s30, v204
	ds_read_b128 v[232:235], v0
	ds_read_b128 v[236:239], v0 offset:4096
	v_exp_f32_e32 v117, v136
	v_exp_f32_e32 v196, v135
	v_exp_f32_e32 v136, v121
	v_exp_f32_e32 v200, v137
	s_waitcnt lgkmcnt(6)
	v_mfma_f32_32x32x16_bf16 v[80:95], v[224:227], v[148:151], v[80:95]
	ds_read_b128 v[224:227], v0 offset:8192
	ds_read_b128 v[240:243], v0 offset:12288
	v_exp_f32_e32 v0, v113
	v_exp_f32_e32 v113, v114
	v_exp_f32_e32 v114, v130
	v_exp_f32_e32 v244, v139
	v_exp_f32_e32 v119, v140
	v_exp_f32_e32 v140, v125
	s_waitcnt lgkmcnt(7)
	v_mfma_f32_32x32x16_bf16 v[96:111], v[2:5], v[152:155], v[96:111]
	v_exp_f32_e32 v5, v118
	v_exp_f32_e32 v118, v138
	v_exp_f32_e32 v138, v123
	v_exp_f32_e32 v246, v141
	v_exp_f32_e32 v248, v143
	v_add_f32_e32 v161, v112, v7
	v_add_f32_e32 v163, v114, v113
	s_waitcnt lgkmcnt(6)
	v_mfma_f32_32x32x16_bf16 v[80:95], v[8:11], v[152:155], v[80:95]
	v_add_f32_e32 v165, v128, v116
	v_add_f32_e32 v197, v115, v5
	v_cvt_pk_bf16_f32 v2, v7, v0
	v_cvt_pk_bf16_f32 v3, v113, v132
	v_cvt_pk_bf16_f32 v4, v116, v134
	v_cvt_pk_bf16_f32 v5, v5, v198
	v_cvt_pk_bf16_f32 v113, v118, v244
	s_waitcnt lgkmcnt(5)
	v_mfma_f32_32x32x16_bf16 v[96:111], v[12:15], v[156:159], v[96:111]
	v_exp_f32_e32 v12, v120
	v_exp_f32_e32 v13, v122
	v_exp_f32_e32 v14, v124
	v_exp_f32_e32 v15, v126
	v_exp_f32_e32 v120, v142
	v_exp_f32_e32 v142, v127
	v_add_f32_e32 v201, v117, v12
	s_waitcnt lgkmcnt(4)
	v_mfma_f32_32x32x16_bf16 v[80:95], v[228:231], v[156:159], v[80:95]
	v_add_f32_e32 v245, v118, v13
	v_add_f32_e32 v247, v119, v14
	v_add_f32_e32 v249, v120, v15
	v_cvt_pk_bf16_f32 v8, v12, v136
	v_cvt_pk_bf16_f32 v9, v13, v138
	v_cvt_pk_bf16_f32 v10, v14, v140
	v_cvt_pk_bf16_f32 v11, v15, v142
	v_cvt_pk_bf16_f32 v12, v112, v160
	v_cvt_pk_bf16_f32 v13, v114, v162
	v_cvt_pk_bf16_f32 v14, v128, v164
	v_cvt_pk_bf16_f32 v15, v115, v196
	v_cvt_pk_bf16_f32 v112, v117, v200
	v_cvt_pk_bf16_f32 v114, v119, v246
	v_cvt_pk_bf16_f32 v115, v120, v248
	v_add_f32_e32 v160, v160, v0
	v_add_f32_e32 v161, v161, v1
	v_add_u32_e32 v7, s30, v220
	v_add_f32_e32 v161, v160, v161
	v_add_f32_e32 v160, v160, v160
	v_mov_b32_e32 v133, v161
	v_add_f32_e32 v132, v162, v132
	v_add_f32_e32 v133, v163, v133
	s_waitcnt lgkmcnt(3)
	v_mfma_f32_32x32x16_bf16 v[64:79], v[232:235], v[2:5], v[64:79]
	v_add_f32_e32 v135, v132, v133
	v_add_f32_e32 v132, v164, v134
	v_add_f32_e32 v133, v165, v135
	ds_read_b128 v[116:119], v7
	ds_read_b128 v[120:123], v7 offset:4096
	ds_read_b128 v[124:127], v7 offset:8192
	ds_read_b128 v[128:131], v7 offset:12288
	v_add_f32_e32 v199, v132, v133
	v_add_f32_e32 v132, v196, v198
	v_add_f32_e32 v133, v197, v199
	s_waitcnt lgkmcnt(6)
	v_mfma_f32_32x32x16_bf16 v[48:63], v[236:239], v[2:5], v[48:63]
	v_add_f32_e32 v137, v132, v133
	v_add_f32_e32 v132, v200, v136
	v_add_f32_e32 v133, v201, v137
	s_nop 0
	v_add_f32_e32 v139, v132, v133
	v_add_f32_e32 v132, v244, v138
	v_add_f32_e32 v133, v245, v139
	s_waitcnt lgkmcnt(5)
	v_mfma_f32_32x32x16_bf16 v[32:47], v[224:227], v[2:5], v[32:47]
	v_add_f32_e32 v141, v132, v133
	v_add_f32_e32 v132, v246, v140
	v_add_f32_e32 v133, v247, v141
	s_nop 0
	v_add_f32_e32 v143, v132, v133
	v_add_f32_e32 v132, v248, v142
	v_add_f32_e32 v133, v249, v143
	s_waitcnt lgkmcnt(4)
	v_mfma_f32_32x32x16_bf16 v[16:31], v[240:243], v[2:5], v[16:31]
	v_add_f32_e32 v0, v132, v133
	v_add_f32_e32 v184, v6, v0
	s_waitcnt lgkmcnt(3)
	v_mfma_f32_32x32x16_bf16 v[64:79], v[116:119], v[8:11], v[64:79]
	v_add_u32_e32 v0, s30, v221
	s_waitcnt lgkmcnt(2)
	v_mfma_f32_32x32x16_bf16 v[48:63], v[120:123], v[8:11], v[48:63]
	s_waitcnt lgkmcnt(1)
	v_mfma_f32_32x32x16_bf16 v[32:47], v[124:127], v[8:11], v[32:47]
	ds_read_b128 v[2:5], v0
	ds_read_b128 v[116:119], v0 offset:4096
	ds_read_b128 v[120:123], v0 offset:8192
	ds_read_b128 v[124:127], v0 offset:12288
	s_waitcnt lgkmcnt(4)
	v_mfma_f32_32x32x16_bf16 v[16:31], v[128:131], v[8:11], v[16:31]
	v_add_u32_e32 v0, s30, v222
	ds_read_b128 v[6:9], v0
	ds_read_b128 v[128:131], v0 offset:4096
	s_waitcnt lgkmcnt(5)
	v_mfma_f32_32x32x16_bf16 v[64:79], v[2:5], v[12:15], v[64:79]
	ds_read_b128 v[2:5], v0 offset:8192
	ds_read_b128 v[132:135], v0 offset:12288
	v_max_f32_e32 v0, v97, v97
	v_max_f32_e32 v10, v81, v81
	v_max_f32_e32 v0, v0, v10
	v_max3_f32 v10, v96, v80, v98
	v_max3_f32 v0, v0, v99, v83
	v_max3_f32 v10, v10, v82, v100
	v_max3_f32 v0, v0, v101, v85
	s_waitcnt lgkmcnt(6)
	v_mfma_f32_32x32x16_bf16 v[48:63], v[116:119], v[12:15], v[48:63]
	v_max3_f32 v10, v10, v84, v102
	v_max3_f32 v0, v0, v103, v87
	v_max3_f32 v10, v10, v86, v104
	v_max3_f32 v0, v0, v105, v89
	v_max3_f32 v10, v10, v88, v106
	v_max3_f32 v0, v0, v107, v91
	v_max3_f32 v10, v10, v90, v108
	s_waitcnt lgkmcnt(5)
	v_mfma_f32_32x32x16_bf16 v[32:47], v[120:123], v[12:15], v[32:47]
	v_max3_f32 v0, v0, v109, v93
	v_max3_f32 v10, v10, v92, v110
	v_max3_f32 v0, v0, v111, v95
	v_max3_f32 v0, v10, v94, v0
	v_mov_b32_e32 v10, v0
	s_nop 1
	v_permlane32_swap_b32_e32 v0, v10
	s_waitcnt lgkmcnt(4)
	v_mfma_f32_32x32x16_bf16 v[16:31], v[124:127], v[12:15], v[16:31]
	s_waitcnt lgkmcnt(3)
	v_mfma_f32_32x32x16_bf16 v[64:79], v[6:9], v[112:115], v[64:79]
	v_max_f32_e32 v0, v0, v0
	s_waitcnt lgkmcnt(2)
	v_mfma_f32_32x32x16_bf16 v[48:63], v[128:131], v[112:115], v[48:63]
	s_waitcnt lgkmcnt(1)
	v_mfma_f32_32x32x16_bf16 v[32:47], v[2:5], v[112:115], v[32:47]
	v_max_f32_e32 v2, v10, v10
	v_max_f32_e32 v0, v0, v2
	v_cmp_lt_f32_e32 vcc, s93, v0
	s_waitcnt lgkmcnt(0)
	v_mfma_f32_32x32x16_bf16 v[16:31], v[132:135], v[112:115], v[16:31]
	s_cbranch_vccz .LBB0_597
	v_max_f32_e32 v0, v0, v0
	v_max_f32_e32 v2, 0, v0
	v_exp_f32_e64 v0, -v2
	v_add_f32_e32 v169, v169, v2
	v_sub_f32_e32 v111, v111, v2
	v_sub_f32_e32 v110, v110, v2
	v_pk_mul_f32 v[78:79], v[78:79], v[0:1] op_sel_hi:[1,0]
	v_pk_mul_f32 v[76:77], v[76:77], v[0:1] op_sel_hi:[1,0]
	v_pk_mul_f32 v[74:75], v[74:75], v[0:1] op_sel_hi:[1,0]
	v_pk_mul_f32 v[72:73], v[72:73], v[0:1] op_sel_hi:[1,0]
	v_pk_mul_f32 v[70:71], v[70:71], v[0:1] op_sel_hi:[1,0]
	v_pk_mul_f32 v[68:69], v[68:69], v[0:1] op_sel_hi:[1,0]
	v_pk_mul_f32 v[66:67], v[66:67], v[0:1] op_sel_hi:[1,0]
	v_pk_mul_f32 v[64:65], v[64:65], v[0:1] op_sel_hi:[1,0]
	v_pk_mul_f32 v[62:63], v[62:63], v[0:1] op_sel_hi:[1,0]
	v_pk_mul_f32 v[60:61], v[60:61], v[0:1] op_sel_hi:[1,0]
	v_pk_mul_f32 v[58:59], v[58:59], v[0:1] op_sel_hi:[1,0]
	v_pk_mul_f32 v[56:57], v[56:57], v[0:1] op_sel_hi:[1,0]
	v_pk_mul_f32 v[54:55], v[54:55], v[0:1] op_sel_hi:[1,0]
	v_pk_mul_f32 v[52:53], v[52:53], v[0:1] op_sel_hi:[1,0]
	v_pk_mul_f32 v[50:51], v[50:51], v[0:1] op_sel_hi:[1,0]
	v_pk_mul_f32 v[48:49], v[48:49], v[0:1] op_sel_hi:[1,0]
	v_pk_mul_f32 v[46:47], v[0:1], v[46:47] op_sel_hi:[0,1]
	v_pk_mul_f32 v[44:45], v[0:1], v[44:45] op_sel_hi:[0,1]
	v_pk_mul_f32 v[42:43], v[0:1], v[42:43] op_sel_hi:[0,1]
	v_pk_mul_f32 v[40:41], v[0:1], v[40:41] op_sel_hi:[0,1]
	v_pk_mul_f32 v[38:39], v[0:1], v[38:39] op_sel_hi:[0,1]
	v_pk_mul_f32 v[36:37], v[0:1], v[36:37] op_sel_hi:[0,1]
	v_pk_mul_f32 v[34:35], v[0:1], v[34:35] op_sel_hi:[0,1]
	v_pk_mul_f32 v[32:33], v[0:1], v[32:33] op_sel_hi:[0,1]
	v_pk_mul_f32 v[30:31], v[0:1], v[30:31] op_sel_hi:[0,1]
	v_pk_mul_f32 v[28:29], v[0:1], v[28:29] op_sel_hi:[0,1]
	v_pk_mul_f32 v[26:27], v[0:1], v[26:27] op_sel_hi:[0,1]
	v_pk_mul_f32 v[24:25], v[0:1], v[24:25] op_sel_hi:[0,1]
	v_pk_mul_f32 v[22:23], v[0:1], v[22:23] op_sel_hi:[0,1]
	v_pk_mul_f32 v[20:21], v[0:1], v[20:21] op_sel_hi:[0,1]
	v_pk_mul_f32 v[18:19], v[0:1], v[18:19] op_sel_hi:[0,1]
	v_pk_mul_f32 v[16:17], v[0:1], v[16:17] op_sel_hi:[0,1]
	v_sub_f32_e32 v109, v109, v2
	v_sub_f32_e32 v108, v108, v2
	v_sub_f32_e32 v107, v107, v2
	v_sub_f32_e32 v106, v106, v2
	v_sub_f32_e32 v105, v105, v2
	v_sub_f32_e32 v104, v104, v2
	v_sub_f32_e32 v103, v103, v2
	v_sub_f32_e32 v102, v102, v2
	v_sub_f32_e32 v101, v101, v2
	v_sub_f32_e32 v100, v100, v2
	v_sub_f32_e32 v99, v99, v2
	v_sub_f32_e32 v98, v98, v2
	v_sub_f32_e32 v97, v97, v2
	v_sub_f32_e32 v96, v96, v2
	v_sub_f32_e32 v95, v95, v2
	v_sub_f32_e32 v94, v94, v2
	v_sub_f32_e32 v93, v93, v2
	v_sub_f32_e32 v92, v92, v2
	v_sub_f32_e32 v91, v91, v2
	v_sub_f32_e32 v90, v90, v2
	v_sub_f32_e32 v89, v89, v2
	v_sub_f32_e32 v88, v88, v2
	v_sub_f32_e32 v87, v87, v2
	v_sub_f32_e32 v86, v86, v2
	v_sub_f32_e32 v85, v85, v2
	v_sub_f32_e32 v84, v84, v2
	v_sub_f32_e32 v83, v83, v2
	v_sub_f32_e32 v82, v82, v2
	v_sub_f32_e32 v81, v81, v2
	v_sub_f32_e32 v80, v80, v2
	v_mul_f32_e32 v184, v184, v0
